# XCD-local seams v2: decision cached in LDS at ph6 entry, L1 invalidate issued before the arrival atomic at local seams (no invalidate after release)
# baseline (speedup 1.0000x reference)
; #define SEAM(k) do { if (IN((k) + 1)) grid.sync(); } while (0)
; #define SEAM(k) do { if (hi > (k) + 1) { if (lo > hi) grid.sync(); xcd_barrier(bar); } } while (0)
; __global__ void __launch_bounds__(NTHR, 2) hybrid_fwd(Args args) {
;     ...
;     if (IN(6)) { BODY6; if (PROBE_ID == 106) BODY6; SEAM(6); }
.LBB0_584:
	s_cmp_lt_i32 s80, 7
	s_cselect_b64 s[0:1], -1, 0
	s_cmp_gt_i32 s81, 6
	s_cselect_b64 s[2:3], -1, 0
	s_and_b64 s[0:1], s[0:1], s[2:3]
	s_andn2_b64 vcc, exec, s[0:1]
	s_cbranch_vccnz .LBB0_681
	v_readfirstlane_b32 s98, v0
	s_cmp_lt_u32 s98, 64
	s_cbranch_scc0 .Lxl_set
	s_add_u32 s100, s78, 0x4120
	s_addc_u32 s101, s79, 0
	s_mov_b64 exec, 1
	v_mov_b32_e32 v1, 0
	global_load_dword v2, v1, s[100:101] sc1
	s_waitcnt vmcnt(0)
	v_cmp_eq_u32_e32 vcc, 0, v2
	v_cndmask_b32_e64 v2, 2, 1, vcc
	v_mov_b32_e32 v1, 0x20008
	ds_write_b32 v1, v2
	s_waitcnt lgkmcnt(0)
	s_mov_b64 exec, -1

; __device__ __forceinline__ unsigned xb_add(unsigned* p, unsigned v) { return __hip_atomic_fetch_add(p, v, __ATOMIC_RELAXED, __HIP_MEMORY_SCOPE_AGENT); }
; __device__ __forceinline__ void xcd_barrier(const XcdBarrier& b) {
;     asm volatile("s_waitcnt vmcnt(0)" ::: "memory");
;     __syncthreads();
;     if (threadIdx.x == 0) {
;         unsigned* bar = b.bar;
;         __builtin_amdgcn_s_waitcnt(0);
;         unsigned nloc = b.st[0], nx = b.st[1];
;         if (nloc == 0u) { xcd_barrier_complete(bar, b.x, nloc, nx); b.st[0] = nloc; b.st[1] = nx; }
;         const unsigned old = xb_add(&bar[XB_XSUB(b.x)], 1u);
.LBB0_628:
	s_waitcnt vmcnt(0)
	s_waitcnt lgkmcnt(0)
	s_barrier
	s_mov_b64 s[4:5], exec
	v_readlane_b32 s0, v254, 1
	v_readlane_b32 s1, v254, 2
	s_and_b64 s[0:1], s[4:5], s[0:1]
	s_mov_b64 exec, s[0:1]
	s_cbranch_execz .LBB0_680
	s_add_i32 s0, 0, 0x20000
	v_mov_b32_e32 v1, s0
	s_waitcnt vmcnt(0) expcnt(0) lgkmcnt(0)
	ds_read_b32 v3, v1
	s_add_i32 s0, 0, 0x20004
	v_mov_b32_e32 v1, s0
	ds_read_b32 v1, v1
	v_mov_b32_e32 v2, 0x20008
	ds_read_b32 v2, v2
	s_waitcnt lgkmcnt(0)
	v_readfirstlane_b32 s101, v2
	s_cmp_eq_u32 s101, 1
	s_cbranch_scc0 .Lxm_0
	buffer_inv sc1
.Lxm_0:
	s_waitcnt lgkmcnt(1)
	v_cmp_ne_u32_e32 vcc, 0, v3
	s_cbranch_vccnz .LBB0_644
	s_add_u32 s6, s78, 0x4200
	s_addc_u32 s7, s79, 0
	s_add_u32 s8, s78, 0x4400
	s_addc_u32 s9, s79, 0
	s_add_u32 s10, s78, 0x4500
	s_addc_u32 s11, s79, 0
	s_add_u32 s12, s78, 0x4600
	s_addc_u32 s13, s79, 0
	s_add_u32 s14, s78, 0x4700
	s_addc_u32 s15, s79, 0
	s_add_u32 s16, s78, 0x4800
	s_addc_u32 s17, s79, 0
	s_add_u32 s18, s78, 0x4900
	s_addc_u32 s19, s79, 0
	s_add_u32 s20, s78, 0x4a00
	s_addc_u32 s21, s79, 0
	s_add_u32 s22, s78, 0x4b00
	s_addc_u32 s23, s79, 0
	s_add_u32 s24, s78, 0x4c00
	s_addc_u32 s25, s79, 0
	s_add_u32 s26, s78, 0x4d00
	s_addc_u32 s27, s79, 0
	s_add_u32 s28, s78, 0x4e00
	s_addc_u32 s29, s79, 0
	s_add_u32 s30, s78, 0x4f00
	s_addc_u32 s31, s79, 0
	s_add_u32 s34, s78, 0x5000
	s_addc_u32 s35, s79, 0
	s_add_u32 s36, s78, 0x5100
	s_addc_u32 s37, s79, 0
	s_add_u32 s38, s78, 0x5200
	v_readlane_b32 s0, v254, 0
	s_addc_u32 s39, s79, 0
	s_mul_i32 s0, s83, s0
	s_add_u32 s40, s78, 0x5300
	s_mul_i32 s0, s0, s82
	s_addc_u32 s41, s79, 0
	s_mov_b32 s1, 1
	v_mov_b32_e32 v17, 0
	s_branch .LBB0_632

; __device__ __forceinline__ unsigned xb_ld(unsigned* p)              { return __hip_atomic_load(p, __ATOMIC_RELAXED, __HIP_MEMORY_SCOPE_AGENT); }
; #define XB_SPIN(cond, bar) do { unsigned _sp = 0; while (cond) { __builtin_amdgcn_s_sleep(1); \
;     if ((++_sp & 255u) == 0u) { if (xb_ld(&(bar)[XB_TMO])) break; if (_sp > XB_SPIN_CAP) { atomicAdd(&(bar)[XB_TMO], 1u); break; } } } } while (0)
; __device__ __forceinline__ void xcd_barrier(const XcdBarrier& b) {
;     ...
;         } else {
;             XB_SPIN(xb_ld(&bar[XB_XGEN(b.x)]) == gen, bar);
;             __builtin_amdgcn_fence(__ATOMIC_ACQUIRE, "agent");
;             asm volatile("s_waitcnt vmcnt(0)" ::: "memory");
.LBB0_659:
	s_or_b64 exec, exec, s[10:11]
	s_waitcnt vmcnt(0)
	s_cmp_eq_u32 s101, 1
	s_cbranch_scc1 .Lxn_0
	buffer_inv sc1

; __device__ __forceinline__ unsigned xb_add(unsigned* p, unsigned v) { return __hip_atomic_fetch_add(p, v, __ATOMIC_RELAXED, __HIP_MEMORY_SCOPE_AGENT); }
; __device__ __forceinline__ void xcd_barrier(const XcdBarrier& b) {
;     ...
;         if (old + 1u == (gen + 1u) * nloc) {
;             __builtin_amdgcn_fence(__ATOMIC_RELEASE, "agent");
;             asm volatile("s_waitcnt vmcnt(0)" ::: "memory");
;             const unsigned og = xb_add(&bar[XB_TOP], 1u);
;             const unsigned tg = og / nx;
;             if (og + 1u == (tg + 1u) * nx) xb_add(&bar[XB_TOPGEN], 1u);
.LBB0_660:
	s_andn2_saveexec_b64 s[0:1], s[8:9]
	s_cbranch_execz .LBB0_680
	s_mov_b64 s[8:9], exec
	s_cmp_eq_u32 s101, 1
	s_cbranch_scc1 .LBB0_677
	buffer_wbl2 sc1
	s_waitcnt lgkmcnt(0)
	s_waitcnt vmcnt(0)
	v_mbcnt_lo_u32_b32 v2, s8, 0
	v_mbcnt_hi_u32_b32 v2, s9, v2
	v_cmp_eq_u32_e32 vcc, 0, v2
	s_and_saveexec_b64 s[10:11], vcc
	s_cbranch_execz .LBB0_663
	s_bcnt1_i32_b64 s0, s[8:9]
	v_mov_b32_e32 v3, 0x7000
	v_mov_b32_e32 v4, s0
	global_atomic_add v3, v3, v4, s[78:79] offset:1024 sc0

; __device__ __forceinline__ unsigned xb_add(unsigned* p, unsigned v) { return __hip_atomic_fetch_add(p, v, __ATOMIC_RELAXED, __HIP_MEMORY_SCOPE_AGENT); }
; __device__ __forceinline__ void xcd_barrier(const XcdBarrier& b) {
;     ...
;             __builtin_amdgcn_fence(__ATOMIC_ACQUIRE, "agent");
;             xb_add(&bar[XB_XGEN(b.x)], 1u);
;             asm volatile("s_waitcnt vmcnt(0)" ::: "memory");
.LBB0_677:
	s_or_b64 exec, exec, s[8:9]
	s_mov_b64 s[8:9], exec
	v_mbcnt_lo_u32_b32 v1, s8, 0
	v_mbcnt_hi_u32_b32 v1, s9, v1
	v_cmp_eq_u32_e32 vcc, 0, v1
	s_cmp_eq_u32 s101, 1
	s_cbranch_scc1 .Lxr_0
	s_waitcnt vmcnt(0)
	buffer_inv sc1
.Lxr_0:
	s_and_saveexec_b64 s[10:11], vcc
	s_cbranch_execz .LBB0_679
	s_bcnt1_i32_b64 s0, s[8:9]
	v_mov_b32_e32 v1, 0x2000
	v_mov_b32_e32 v2, s0
	global_atomic_add v1, v2, s[6:7] offset:1024

; __device__ __forceinline__ unsigned xb_add(unsigned* p, unsigned v) { return __hip_atomic_fetch_add(p, v, __ATOMIC_RELAXED, __HIP_MEMORY_SCOPE_AGENT); }
; __device__ __forceinline__ void xcd_barrier(const XcdBarrier& b) {
;     asm volatile("s_waitcnt vmcnt(0)" ::: "memory");
;     __syncthreads();
;     if (threadIdx.x == 0) {
;         unsigned* bar = b.bar;
;         __builtin_amdgcn_s_waitcnt(0);
;         unsigned nloc = b.st[0], nx = b.st[1];
;         if (nloc == 0u) { xcd_barrier_complete(bar, b.x, nloc, nx); b.st[0] = nloc; b.st[1] = nx; }
;         const unsigned old = xb_add(&bar[XB_XSUB(b.x)], 1u);
.LBB0_698:
	s_cmp_lt_i32 s81, 9
	s_cbranch_scc1 .LBB0_752
	s_waitcnt vmcnt(0)
	s_waitcnt lgkmcnt(0)
	s_barrier
	s_mov_b64 s[4:5], exec
	v_readlane_b32 s0, v254, 1
	v_readlane_b32 s1, v254, 2
	s_and_b64 s[0:1], s[4:5], s[0:1]
	s_mov_b64 exec, s[0:1]
	s_cbranch_execz .LBB0_751
	s_add_i32 s0, 0, 0x20000
	v_mov_b32_e32 v1, s0
	s_waitcnt vmcnt(0) expcnt(0) lgkmcnt(0)
	ds_read_b32 v3, v1
	s_add_i32 s0, 0, 0x20004
	v_mov_b32_e32 v1, s0
	ds_read_b32 v1, v1
	v_mov_b32_e32 v2, 0x20008
	ds_read_b32 v2, v2
	s_waitcnt lgkmcnt(0)
	v_readfirstlane_b32 s101, v2
	s_cmp_eq_u32 s101, 1
	s_cbranch_scc0 .Lxm_1
	buffer_inv sc1

; __device__ __forceinline__ unsigned xb_add(unsigned* p, unsigned v) { return __hip_atomic_fetch_add(p, v, __ATOMIC_RELAXED, __HIP_MEMORY_SCOPE_AGENT); }
; __device__ __forceinline__ void xcd_barrier(const XcdBarrier& b) {
;     asm volatile("s_waitcnt vmcnt(0)" ::: "memory");
;     __syncthreads();
;     if (threadIdx.x == 0) {
;         unsigned* bar = b.bar;
;         __builtin_amdgcn_s_waitcnt(0);
;         unsigned nloc = b.st[0], nx = b.st[1];
;         if (nloc == 0u) { xcd_barrier_complete(bar, b.x, nloc, nx); b.st[0] = nloc; b.st[1] = nx; }
;         const unsigned old = xb_add(&bar[XB_XSUB(b.x)], 1u);
.LBB0_828:
	s_cmp_lt_i32 s81, 10
	s_cbranch_scc1 .LBB0_882
	s_waitcnt vmcnt(0)
	s_waitcnt vmcnt(0) lgkmcnt(0)
	s_barrier
	s_mov_b64 s[4:5], exec
	v_readlane_b32 s0, v254, 1
	v_readlane_b32 s1, v254, 2
	s_and_b64 s[0:1], s[4:5], s[0:1]
	s_mov_b64 exec, s[0:1]
	s_cbranch_execz .LBB0_881
	s_add_i32 s0, 0, 0x20000
	v_mov_b32_e32 v1, s0
	s_waitcnt vmcnt(0) expcnt(0) lgkmcnt(0)
	ds_read_b32 v3, v1
	s_add_i32 s0, 0, 0x20004
	v_mov_b32_e32 v1, s0
	ds_read_b32 v1, v1
	v_mov_b32_e32 v2, 0x20008
	ds_read_b32 v2, v2
	s_waitcnt lgkmcnt(0)
	v_readfirstlane_b32 s101, v2
	s_cmp_eq_u32 s101, 1
	s_cbranch_scc0 .Lxm_2
	buffer_inv sc1

; __device__ __forceinline__ unsigned xb_add(unsigned* p, unsigned v) { return __hip_atomic_fetch_add(p, v, __ATOMIC_RELAXED, __HIP_MEMORY_SCOPE_AGENT); }
; __device__ __forceinline__ void xcd_barrier(const XcdBarrier& b) {
;     asm volatile("s_waitcnt vmcnt(0)" ::: "memory");
;     __syncthreads();
;     if (threadIdx.x == 0) {
;         unsigned* bar = b.bar;
;         __builtin_amdgcn_s_waitcnt(0);
;         unsigned nloc = b.st[0], nx = b.st[1];
;         if (nloc == 0u) { xcd_barrier_complete(bar, b.x, nloc, nx); b.st[0] = nloc; b.st[1] = nx; }
;         const unsigned old = xb_add(&bar[XB_XSUB(b.x)], 1u);
.LBB0_1000:
	s_cmp_lt_i32 s81, 12
	s_cbranch_scc1 .LBB0_1054
	s_waitcnt vmcnt(0)
	s_waitcnt vmcnt(0) lgkmcnt(0)
	s_barrier
	s_mov_b64 s[4:5], exec
	v_readlane_b32 s0, v254, 1
	v_readlane_b32 s1, v254, 2
	s_and_b64 s[0:1], s[4:5], s[0:1]
	s_mov_b64 exec, s[0:1]
	s_cbranch_execz .LBB0_1053
	s_add_i32 s0, 0, 0x20000
	v_mov_b32_e32 v1, s0
	s_waitcnt vmcnt(0) expcnt(0) lgkmcnt(0)
	ds_read_b32 v3, v1
	s_add_i32 s0, 0, 0x20004
	v_mov_b32_e32 v1, s0
	ds_read_b32 v1, v1
	v_mov_b32_e32 v2, 0x20008
	ds_read_b32 v2, v2
	s_waitcnt lgkmcnt(0)
	v_readfirstlane_b32 s101, v2
	s_cmp_eq_u32 s101, 1
	s_cbranch_scc0 .Lxm_3
	buffer_inv sc1

; __device__ __forceinline__ unsigned xb_add(unsigned* p, unsigned v) { return __hip_atomic_fetch_add(p, v, __ATOMIC_RELAXED, __HIP_MEMORY_SCOPE_AGENT); }
; __device__ __forceinline__ void xcd_barrier(const XcdBarrier& b) {
;     asm volatile("s_waitcnt vmcnt(0)" ::: "memory");
;     __syncthreads();
;     if (threadIdx.x == 0) {
;         unsigned* bar = b.bar;
;         __builtin_amdgcn_s_waitcnt(0);
;         unsigned nloc = b.st[0], nx = b.st[1];
;         if (nloc == 0u) { xcd_barrier_complete(bar, b.x, nloc, nx); b.st[0] = nloc; b.st[1] = nx; }
;         const unsigned old = xb_add(&bar[XB_XSUB(b.x)], 1u);
.LBB0_1393:
	s_waitcnt vmcnt(0)
	s_barrier
	s_mov_b64 s[4:5], exec
	v_readlane_b32 s0, v254, 1
	v_readlane_b32 s1, v254, 2
	s_and_b64 s[0:1], s[4:5], s[0:1]
	s_mov_b64 exec, s[0:1]
	s_cbranch_execz .LBB0_1445
	s_add_i32 s0, 0, 0x20000
	v_mov_b32_e32 v1, s0
	s_waitcnt vmcnt(0) expcnt(0) lgkmcnt(0)
	ds_read_b32 v3, v1
	s_add_i32 s0, 0, 0x20004
	v_mov_b32_e32 v1, s0
	ds_read_b32 v1, v1
	v_mov_b32_e32 v2, 0x20008
	ds_read_b32 v2, v2
	s_waitcnt lgkmcnt(0)
	v_readfirstlane_b32 s101, v2
	s_cmp_eq_u32 s101, 1
	s_cbranch_scc0 .Lxm_4
	buffer_inv sc1

; __device__ __forceinline__ unsigned xb_add(unsigned* p, unsigned v) { return __hip_atomic_fetch_add(p, v, __ATOMIC_RELAXED, __HIP_MEMORY_SCOPE_AGENT); }
; __device__ __forceinline__ void xcd_barrier(const XcdBarrier& b) {
;     asm volatile("s_waitcnt vmcnt(0)" ::: "memory");
;     __syncthreads();
;     if (threadIdx.x == 0) {
;         unsigned* bar = b.bar;
;         __builtin_amdgcn_s_waitcnt(0);
;         unsigned nloc = b.st[0], nx = b.st[1];
;         if (nloc == 0u) { xcd_barrier_complete(bar, b.x, nloc, nx); b.st[0] = nloc; b.st[1] = nx; }
;         const unsigned old = xb_add(&bar[XB_XSUB(b.x)], 1u);
.LBB0_1560:
	s_cmp_lt_i32 s81, 16
	s_cbranch_scc1 .LBB0_1614
	s_waitcnt vmcnt(0)
	s_waitcnt vmcnt(0) lgkmcnt(0)
	s_barrier
	s_mov_b64 s[4:5], exec
	v_readlane_b32 s0, v254, 1
	v_readlane_b32 s1, v254, 2
	s_and_b64 s[0:1], s[4:5], s[0:1]
	s_mov_b64 exec, s[0:1]
	s_cbranch_execz .LBB0_1613
	s_add_i32 s0, 0, 0x20000
	v_mov_b32_e32 v1, s0
	s_waitcnt vmcnt(0) expcnt(0) lgkmcnt(0)
	ds_read_b32 v3, v1
	s_add_i32 s0, 0, 0x20004
	v_mov_b32_e32 v1, s0
	ds_read_b32 v1, v1
	v_mov_b32_e32 v2, 0x20008
	ds_read_b32 v2, v2
	s_waitcnt lgkmcnt(0)
	v_readfirstlane_b32 s101, v2
	s_cmp_eq_u32 s101, 1
	s_cbranch_scc0 .Lxm_5
	buffer_inv sc1

; __device__ __forceinline__ unsigned xb_add(unsigned* p, unsigned v) { return __hip_atomic_fetch_add(p, v, __ATOMIC_RELAXED, __HIP_MEMORY_SCOPE_AGENT); }
; __device__ __forceinline__ void xcd_barrier(const XcdBarrier& b) {
;     asm volatile("s_waitcnt vmcnt(0)" ::: "memory");
;     __syncthreads();
;     if (threadIdx.x == 0) {
;         unsigned* bar = b.bar;
;         __builtin_amdgcn_s_waitcnt(0);
;         unsigned nloc = b.st[0], nx = b.st[1];
;         if (nloc == 0u) { xcd_barrier_complete(bar, b.x, nloc, nx); b.st[0] = nloc; b.st[1] = nx; }
;         const unsigned old = xb_add(&bar[XB_XSUB(b.x)], 1u);
.LBB0_1690:
	s_cmp_lt_i32 s81, 17
	s_cbranch_scc1 .LBB0_1744
	s_waitcnt vmcnt(0)
	s_waitcnt vmcnt(0) lgkmcnt(0)
	s_barrier
	s_mov_b64 s[4:5], exec
	v_readlane_b32 s0, v254, 1
	v_readlane_b32 s1, v254, 2
	s_and_b64 s[0:1], s[4:5], s[0:1]
	s_mov_b64 exec, s[0:1]
	s_cbranch_execz .LBB0_1743
	s_add_i32 s0, 0, 0x20000
	v_mov_b32_e32 v1, s0
	s_waitcnt vmcnt(0) expcnt(0) lgkmcnt(0)
	ds_read_b32 v3, v1
	s_add_i32 s0, 0, 0x20004
	v_mov_b32_e32 v1, s0
	ds_read_b32 v1, v1
	v_mov_b32_e32 v2, 0x20008
	ds_read_b32 v2, v2
	s_waitcnt lgkmcnt(0)
	v_readfirstlane_b32 s101, v2
	s_cmp_eq_u32 s101, 1
	s_cbranch_scc0 .Lxm_6
	buffer_inv sc1
